# v67 plus attention tile loop: the 32 bias-table pointer advances skipped once the local (biased) tiles of the item are done
# speedup vs baseline: 1.0046x; 1.0039x over previous
.LBB0_263:
	s_or_b64 exec, exec, s[36:37]
	s_add_i32 s54, s54, 1
	s_addk_i32 s53, 0x4000
	s_add_i32 s76, s76, 64
	s_add_i32 s25, s25, 1
	s_add_i32 s52, s52, -1
	v_cmp_ge_i32_e32 vcc, s54, v123
	s_cmp_lg_u64 vcc, 0
	v_cmp_eq_u32_e32 vcc, s54, v121
	s_cbranch_scc1 .Lbt_skip
	v_add_u32_e32 v131, 0x80, v131
	v_add_u32_e32 v132, 0x80, v132
	v_add_u32_e32 v133, 0x80, v133
	v_add_u32_e32 v134, 0x80, v134
	v_add_u32_e32 v135, 0x80, v135
	v_add_u32_e32 v136, 0x80, v136
	v_add_u32_e32 v137, 0x80, v137
	v_add_u32_e32 v138, 0x80, v138
	v_add_u32_e32 v139, 0x80, v139
	v_add_u32_e32 v140, 0x80, v140
	v_add_u32_e32 v141, 0x80, v141
	v_add_u32_e32 v142, 0x80, v142
	v_add_u32_e32 v143, 0x80, v143
	v_add_u32_e32 v144, 0x80, v144
	v_add_u32_e32 v145, 0x80, v145
	v_add_u32_e32 v146, 0x80, v146
	v_add_u32_e32 v147, 0x80, v147
	v_add_u32_e32 v148, 0x80, v148
	v_add_u32_e32 v149, 0x80, v149
	v_add_u32_e32 v150, 0x80, v150
	v_add_u32_e32 v151, 0x80, v151
	v_add_u32_e32 v152, 0x80, v152
	v_add_u32_e32 v153, 0x80, v153
	v_add_u32_e32 v154, 0x80, v154
	v_add_u32_e32 v155, 0x80, v155
	v_add_u32_e32 v156, 0x80, v156
	v_add_u32_e32 v157, 0x80, v157
	v_add_u32_e32 v158, 0x80, v158
	v_add_u32_e32 v159, 0x80, v159
	v_add_u32_e32 v160, 0x80, v160
	v_add_u32_e32 v161, 0x80, v161
	v_add_u32_e32 v162, 0x80, v162
.Lbt_skip:
	v_lshl_add_u64 v[118:119], v[118:119], 0, s[92:93]
	s_or_b64 s[46:47], vcc, s[46:47]
	v_mov_b32_e32 v177, v59
	v_mov_b32_e32 v186, v4
	s_andn2_b64 exec, exec, s[46:47]
	s_cbranch_execz .LBB0_202
